# XCD barrier: acquire-side buffer_inv issued at arrival (before polling) instead of after the release is seen, for waiters and XCD leaders in all 13 seams
# speedup vs baseline: 1.0174x; 1.0174x over previous
; __device__ __forceinline__ unsigned xb_ld(unsigned* p)              { return __hip_atomic_load(p, __ATOMIC_RELAXED, __HIP_MEMORY_SCOPE_AGENT); }
; __device__ __forceinline__ unsigned xb_add(unsigned* p, unsigned v) { return __hip_atomic_fetch_add(p, v, __ATOMIC_RELAXED, __HIP_MEMORY_SCOPE_AGENT); }
; #define XB_SPIN(cond, bar) do { unsigned _sp = 0; while (cond) { __builtin_amdgcn_s_sleep(1); \
;     if ((++_sp & 255u) == 0u) { if (xb_ld(&(bar)[XB_TMO])) break; if (_sp > XB_SPIN_CAP) { atomicAdd(&(bar)[XB_TMO], 1u); break; } } } } while (0)
; __device__ __forceinline__ void xcd_barrier(const XcdBarrier& b) {
;     ...
;         unsigned nloc = b.st[0], nx = b.st[1];
;         if (nloc == 0u) { xcd_barrier_complete(bar, b.x, nloc, nx); b.st[0] = nloc; b.st[1] = nx; }
;         const unsigned old = xb_add(&bar[XB_XSUB(b.x)], 1u);
;         const unsigned gen = old / nloc;
;         if (old + 1u == (gen + 1u) * nloc) {
;             __builtin_amdgcn_fence(__ATOMIC_RELEASE, "agent");
;             asm volatile("s_waitcnt vmcnt(0)" ::: "memory");
;             const unsigned og = xb_add(&bar[XB_TOP], 1u);
;             const unsigned tg = og / nx;
;             if (og + 1u == (tg + 1u) * nx) xb_add(&bar[XB_TOPGEN], 1u);
;             else XB_SPIN(xb_ld(&bar[XB_TOPGEN]) == tg, bar);
;             __builtin_amdgcn_fence(__ATOMIC_ACQUIRE, "agent");
;             xb_add(&bar[XB_XGEN(b.x)], 1u);
;             asm volatile("s_waitcnt vmcnt(0)" ::: "memory");
;         } else {
;             XB_SPIN(xb_ld(&bar[XB_XGEN(b.x)]) == gen, bar);
;             __builtin_amdgcn_fence(__ATOMIC_ACQUIRE, "agent");
;             asm volatile("s_waitcnt vmcnt(0)" ::: "memory");
.Lxs0_105:
	s_or_b64 exec, exec, s[6:7]
	v_cvt_f32_u32_e32 v4, v2
	s_waitcnt vmcnt(0)
	v_readfirstlane_b32 s4, v3
	v_sub_u32_e32 v3, 0, v2
	v_rcp_iflag_f32_e32 v4, v4
	v_add_u32_e32 v5, s4, v0
	v_mul_f32_e32 v4, 0x4f7ffffe, v4
	v_cvt_u32_f32_e32 v4, v4
	v_mul_lo_u32 v0, v3, v4
	v_mul_hi_u32 v0, v4, v0
	v_add_u32_e32 v0, v4, v0
	v_mul_hi_u32 v0, v5, v0
	v_mul_lo_u32 v3, v0, v2
	v_sub_u32_e32 v3, v5, v3
	v_add_u32_e32 v4, 1, v0
	v_cmp_ge_u32_e32 vcc, v3, v2
	s_nop 1
	v_cndmask_b32_e32 v0, v0, v4, vcc
	v_sub_u32_e32 v4, v3, v2
	v_cndmask_b32_e32 v3, v3, v4, vcc
	v_add_u32_e32 v4, 1, v0
	v_cmp_ge_u32_e32 vcc, v3, v2
	v_add_u32_e32 v3, 1, v5
	s_nop 0
	v_cndmask_b32_e32 v0, v0, v4, vcc
	v_mul_lo_u32 v4, v2, v0
	v_add_u32_e32 v2, v4, v2
	v_cmp_ne_u32_e32 vcc, v3, v2
	s_and_saveexec_b64 s[4:5], vcc
	s_xor_b64 s[4:5], exec, s[4:5]
	s_cbranch_execz .Lxs0_119
	s_waitcnt lgkmcnt(0)
	buffer_inv sc1
	v_mov_b32_e32 v1, 0x2000
	global_load_dword v1, v1, s[2:3] offset:1024 sc1
	s_add_u32 s10, s2, 0x2400
	s_addc_u32 s11, s3, 0
	s_waitcnt vmcnt(0)
	v_cmp_eq_u32_e32 vcc, v1, v0
	s_and_saveexec_b64 s[6:7], vcc
	s_cbranch_execz .Lxs0_118
	v_readlane_b32 s12, v228, 2
	v_readlane_b32 s18, v228, 8
	v_readlane_b32 s13, v228, 3
	v_readlane_b32 s19, v228, 9
	s_add_u32 s8, s18, 0x179ed200
	v_readlane_b32 s14, v228, 4
	v_readlane_b32 s15, v228, 5
	s_addc_u32 s9, s19, 0
	s_mov_b32 s22, 1
	s_mov_b64 s[12:13], 0
	v_mov_b32_e32 v1, 0
	v_readlane_b32 s16, v228, 6
	v_readlane_b32 s17, v228, 7
	s_branch .Lxs0_109

; __device__ __forceinline__ unsigned xb_ld(unsigned* p)              { return __hip_atomic_load(p, __ATOMIC_RELAXED, __HIP_MEMORY_SCOPE_AGENT); }
; #define XB_SPIN(cond, bar) do { unsigned _sp = 0; while (cond) { __builtin_amdgcn_s_sleep(1); \
;     if ((++_sp & 255u) == 0u) { if (xb_ld(&(bar)[XB_TMO])) break; if (_sp > XB_SPIN_CAP) { atomicAdd(&(bar)[XB_TMO], 1u); break; } } } } while (0)
; __device__ __forceinline__ void xcd_barrier(const XcdBarrier& b) {
;     ...
;         } else {
;             XB_SPIN(xb_ld(&bar[XB_XGEN(b.x)]) == gen, bar);
;             __builtin_amdgcn_fence(__ATOMIC_ACQUIRE, "agent");
;             asm volatile("s_waitcnt vmcnt(0)" ::: "memory");
.Lxs0_118:
	s_or_b64 exec, exec, s[6:7]
	s_waitcnt vmcnt(0)
	s_nop 0
	s_waitcnt vmcnt(0)

; __device__ __forceinline__ unsigned xb_ld(unsigned* p)              { return __hip_atomic_load(p, __ATOMIC_RELAXED, __HIP_MEMORY_SCOPE_AGENT); }
; __device__ __forceinline__ unsigned xb_add(unsigned* p, unsigned v) { return __hip_atomic_fetch_add(p, v, __ATOMIC_RELAXED, __HIP_MEMORY_SCOPE_AGENT); }
; #define XB_SPIN(cond, bar) do { unsigned _sp = 0; while (cond) { __builtin_amdgcn_s_sleep(1); \
;     if ((++_sp & 255u) == 0u) { if (xb_ld(&(bar)[XB_TMO])) break; if (_sp > XB_SPIN_CAP) { atomicAdd(&(bar)[XB_TMO], 1u); break; } } } } while (0)
; __device__ __forceinline__ void xcd_barrier(const XcdBarrier& b) {
;     ...
;         if (old + 1u == (gen + 1u) * nloc) {
;             __builtin_amdgcn_fence(__ATOMIC_RELEASE, "agent");
;             asm volatile("s_waitcnt vmcnt(0)" ::: "memory");
;             const unsigned og = xb_add(&bar[XB_TOP], 1u);
;             const unsigned tg = og / nx;
;             if (og + 1u == (tg + 1u) * nx) xb_add(&bar[XB_TOPGEN], 1u);
;             else XB_SPIN(xb_ld(&bar[XB_TOPGEN]) == tg, bar);
;             __builtin_amdgcn_fence(__ATOMIC_ACQUIRE, "agent");
.Lxs0_122:
	s_or_b64 exec, exec, s[6:7]
	buffer_inv sc1
	v_cvt_f32_u32_e32 v3, v1
	s_waitcnt vmcnt(0)
	v_readfirstlane_b32 s4, v2
	v_rcp_iflag_f32_e32 v3, v3
	s_nop 0
	v_add_u32_e32 v0, s4, v0
	v_add_u32_e32 v4, 1, v0
	v_readlane_b32 s4, v228, 2
	v_mul_f32_e32 v2, 0x4f7ffffe, v3
	v_cvt_u32_f32_e32 v2, v2
	v_sub_u32_e32 v3, 0, v1
	v_readlane_b32 s6, v228, 4
	v_readlane_b32 s10, v228, 8
	v_mul_lo_u32 v3, v3, v2
	v_mul_hi_u32 v3, v2, v3
	v_add_u32_e32 v2, v2, v3
	v_mul_hi_u32 v2, v0, v2
	v_mul_lo_u32 v3, v2, v1
	v_sub_u32_e32 v0, v0, v3
	v_add_u32_e32 v5, 1, v2
	v_cmp_ge_u32_e32 vcc, v0, v1
	v_sub_u32_e32 v3, v0, v1
	v_readlane_b32 s7, v228, 5
	v_cndmask_b32_e32 v2, v2, v5, vcc
	v_cndmask_b32_e32 v0, v0, v3, vcc
	v_add_u32_e32 v3, 1, v2
	v_cmp_ge_u32_e32 vcc, v0, v1
	v_readlane_b32 s11, v228, 9
	s_add_u32 s6, s10, 0x179f0500
	v_cndmask_b32_e32 v2, v2, v3, vcc
	v_mul_lo_u32 v0, v1, v2
	v_add_u32_e32 v0, v0, v1
	v_readlane_b32 s8, v228, 6
	v_readlane_b32 s9, v228, 7
	s_addc_u32 s7, s11, 0
	v_cmp_ne_u32_e32 vcc, v4, v0
	v_readlane_b32 s5, v228, 3
	s_mov_b64 s[8:9], -1
	v_mov_b64_e32 v[0:1], s[6:7]
	s_and_saveexec_b64 s[4:5], vcc
	s_cbranch_execz .Lxs0_134
	v_mov_b32_e32 v0, 0
	global_load_dword v1, v0, s[6:7] sc1
	s_mov_b64 s[12:13], 0
	s_waitcnt vmcnt(0)
	v_cmp_eq_u32_e32 vcc, v1, v2
	s_and_saveexec_b64 s[10:11], vcc
	s_cbranch_execz .Lxs0_133
	v_readlane_b32 s12, v228, 2
	v_readlane_b32 s18, v228, 8
	v_readlane_b32 s13, v228, 3
	v_readlane_b32 s19, v228, 9
	s_add_u32 s8, s18, 0x179ed200
	v_readlane_b32 s14, v228, 4
	v_readlane_b32 s15, v228, 5
	s_addc_u32 s9, s19, 0
	s_mov_b32 s22, 1
	s_mov_b64 s[12:13], 0
	v_readlane_b32 s16, v228, 6
	v_readlane_b32 s17, v228, 7
	s_branch .Lxs0_126

; __device__ __forceinline__ unsigned xb_add(unsigned* p, unsigned v) { return __hip_atomic_fetch_add(p, v, __ATOMIC_RELAXED, __HIP_MEMORY_SCOPE_AGENT); }
; __device__ __forceinline__ void xcd_barrier(const XcdBarrier& b) {
;     ...
;             __builtin_amdgcn_fence(__ATOMIC_ACQUIRE, "agent");
;             xb_add(&bar[XB_XGEN(b.x)], 1u);
;             asm volatile("s_waitcnt vmcnt(0)" ::: "memory");
.Lxs0_136:
	s_or_b64 exec, exec, s[4:5]
	s_mov_b64 s[4:5], exec
	v_mbcnt_lo_u32_b32 v0, s4, 0
	v_mbcnt_hi_u32_b32 v0, s5, v0
	v_cmp_eq_u32_e32 vcc, 0, v0
	s_waitcnt vmcnt(0)
	s_nop 0
	s_and_saveexec_b64 s[6:7], vcc
	s_cbranch_execz .Lxs0_138
	s_bcnt1_i32_b64 s4, s[4:5]
	v_mov_b32_e32 v0, 0x2000
	v_mov_b32_e32 v1, s4
	global_atomic_add v0, v1, s[2:3] offset:1024

; __device__ __forceinline__ unsigned xb_ld(unsigned* p)              { return __hip_atomic_load(p, __ATOMIC_RELAXED, __HIP_MEMORY_SCOPE_AGENT); }
; __device__ __forceinline__ unsigned xb_add(unsigned* p, unsigned v) { return __hip_atomic_fetch_add(p, v, __ATOMIC_RELAXED, __HIP_MEMORY_SCOPE_AGENT); }
; #define XB_SPIN(cond, bar) do { unsigned _sp = 0; while (cond) { __builtin_amdgcn_s_sleep(1); \
;     if ((++_sp & 255u) == 0u) { if (xb_ld(&(bar)[XB_TMO])) break; if (_sp > XB_SPIN_CAP) { atomicAdd(&(bar)[XB_TMO], 1u); break; } } } } while (0)
; __device__ __forceinline__ void xcd_barrier(const XcdBarrier& b) {
;     ...
;         unsigned nloc = b.st[0], nx = b.st[1];
;         if (nloc == 0u) { xcd_barrier_complete(bar, b.x, nloc, nx); b.st[0] = nloc; b.st[1] = nx; }
;         const unsigned old = xb_add(&bar[XB_XSUB(b.x)], 1u);
;         const unsigned gen = old / nloc;
;         if (old + 1u == (gen + 1u) * nloc) {
;             __builtin_amdgcn_fence(__ATOMIC_RELEASE, "agent");
;             asm volatile("s_waitcnt vmcnt(0)" ::: "memory");
;             const unsigned og = xb_add(&bar[XB_TOP], 1u);
;             const unsigned tg = og / nx;
;             if (og + 1u == (tg + 1u) * nx) xb_add(&bar[XB_TOPGEN], 1u);
;             else XB_SPIN(xb_ld(&bar[XB_TOPGEN]) == tg, bar);
;             __builtin_amdgcn_fence(__ATOMIC_ACQUIRE, "agent");
;             xb_add(&bar[XB_XGEN(b.x)], 1u);
;             asm volatile("s_waitcnt vmcnt(0)" ::: "memory");
;         } else {
;             XB_SPIN(xb_ld(&bar[XB_XGEN(b.x)]) == gen, bar);
;             __builtin_amdgcn_fence(__ATOMIC_ACQUIRE, "agent");
;             asm volatile("s_waitcnt vmcnt(0)" ::: "memory");
.LBB0_942:
	s_or_b64 exec, exec, s[6:7]
	v_cvt_f32_u32_e32 v4, v2
	s_waitcnt vmcnt(0)
	v_readfirstlane_b32 s4, v3
	v_sub_u32_e32 v3, 0, v2
	v_rcp_iflag_f32_e32 v4, v4
	v_add_u32_e32 v5, s4, v1
	v_mul_f32_e32 v4, 0x4f7ffffe, v4
	v_cvt_u32_f32_e32 v4, v4
	v_mul_lo_u32 v1, v3, v4
	v_mul_hi_u32 v1, v4, v1
	v_add_u32_e32 v1, v4, v1
	v_mul_hi_u32 v1, v5, v1
	v_mul_lo_u32 v3, v1, v2
	v_sub_u32_e32 v3, v5, v3
	v_add_u32_e32 v4, 1, v1
	v_cmp_ge_u32_e32 vcc, v3, v2
	s_nop 1
	v_cndmask_b32_e32 v1, v1, v4, vcc
	v_sub_u32_e32 v4, v3, v2
	v_cndmask_b32_e32 v3, v3, v4, vcc
	v_add_u32_e32 v4, 1, v1
	v_cmp_ge_u32_e32 vcc, v3, v2
	v_add_u32_e32 v3, 1, v5
	s_nop 0
	v_cndmask_b32_e32 v1, v1, v4, vcc
	v_mul_lo_u32 v4, v2, v1
	v_add_u32_e32 v2, v4, v2
	v_cmp_ne_u32_e32 vcc, v3, v2
	s_and_saveexec_b64 s[4:5], vcc
	s_xor_b64 s[4:5], exec, s[4:5]
	s_cbranch_execz .LBB0_956
	s_waitcnt lgkmcnt(0)
	buffer_inv sc1
	v_mov_b32_e32 v0, 0x2000
	global_load_dword v0, v0, s[2:3] offset:1024 sc1
	s_add_u32 s10, s2, 0x2400
	s_addc_u32 s11, s3, 0
	s_waitcnt vmcnt(0)
	v_cmp_eq_u32_e32 vcc, v0, v1
	s_and_saveexec_b64 s[6:7], vcc
	s_cbranch_execz .LBB0_955
	v_readlane_b32 s12, v228, 2
	v_readlane_b32 s18, v228, 8
	v_readlane_b32 s13, v228, 3
	v_readlane_b32 s19, v228, 9
	s_add_u32 s8, s18, 0x179ed200
	v_readlane_b32 s14, v228, 4
	v_readlane_b32 s15, v228, 5
	s_addc_u32 s9, s19, 0
	s_mov_b32 s22, 1
	s_mov_b64 s[12:13], 0
	v_mov_b32_e32 v0, 0
	v_readlane_b32 s16, v228, 6
	v_readlane_b32 s17, v228, 7
	s_branch .LBB0_946

; __device__ __forceinline__ unsigned xb_ld(unsigned* p)              { return __hip_atomic_load(p, __ATOMIC_RELAXED, __HIP_MEMORY_SCOPE_AGENT); }
; __device__ __forceinline__ unsigned xb_add(unsigned* p, unsigned v) { return __hip_atomic_fetch_add(p, v, __ATOMIC_RELAXED, __HIP_MEMORY_SCOPE_AGENT); }
; #define XB_SPIN(cond, bar) do { unsigned _sp = 0; while (cond) { __builtin_amdgcn_s_sleep(1); \
;     if ((++_sp & 255u) == 0u) { if (xb_ld(&(bar)[XB_TMO])) break; if (_sp > XB_SPIN_CAP) { atomicAdd(&(bar)[XB_TMO], 1u); break; } } } } while (0)
; __device__ __forceinline__ void xcd_barrier(const XcdBarrier& b) {
;     ...
;         if (old + 1u == (gen + 1u) * nloc) {
;             __builtin_amdgcn_fence(__ATOMIC_RELEASE, "agent");
;             asm volatile("s_waitcnt vmcnt(0)" ::: "memory");
;             const unsigned og = xb_add(&bar[XB_TOP], 1u);
;             const unsigned tg = og / nx;
;             if (og + 1u == (tg + 1u) * nx) xb_add(&bar[XB_TOPGEN], 1u);
;             else XB_SPIN(xb_ld(&bar[XB_TOPGEN]) == tg, bar);
;             __builtin_amdgcn_fence(__ATOMIC_ACQUIRE, "agent");
.LBB0_959:
	s_or_b64 exec, exec, s[6:7]
	buffer_inv sc1
	v_cvt_f32_u32_e32 v3, v0
	s_waitcnt vmcnt(0)
	v_readfirstlane_b32 s4, v2
	v_rcp_iflag_f32_e32 v3, v3
	s_nop 0
	v_add_u32_e32 v1, s4, v1
	v_add_u32_e32 v4, 1, v1
	v_readlane_b32 s4, v228, 2
	v_mul_f32_e32 v2, 0x4f7ffffe, v3
	v_cvt_u32_f32_e32 v2, v2
	v_sub_u32_e32 v3, 0, v0
	v_readlane_b32 s6, v228, 4
	v_readlane_b32 s10, v228, 8
	v_mul_lo_u32 v3, v3, v2
	v_mul_hi_u32 v3, v2, v3
	v_add_u32_e32 v2, v2, v3
	v_mul_hi_u32 v2, v1, v2
	v_mul_lo_u32 v3, v2, v0
	v_sub_u32_e32 v1, v1, v3
	v_add_u32_e32 v5, 1, v2
	v_cmp_ge_u32_e32 vcc, v1, v0
	v_sub_u32_e32 v3, v1, v0
	v_readlane_b32 s7, v228, 5
	v_cndmask_b32_e32 v2, v2, v5, vcc
	v_cndmask_b32_e32 v1, v1, v3, vcc
	v_add_u32_e32 v3, 1, v2
	v_cmp_ge_u32_e32 vcc, v1, v0
	v_readlane_b32 s11, v228, 9
	s_add_u32 s6, s10, 0x179f0500
	v_cndmask_b32_e32 v2, v2, v3, vcc
	v_mul_lo_u32 v1, v0, v2
	v_add_u32_e32 v0, v1, v0
	v_readlane_b32 s8, v228, 6
	v_readlane_b32 s9, v228, 7
	s_addc_u32 s7, s11, 0
	v_cmp_ne_u32_e32 vcc, v4, v0
	v_readlane_b32 s5, v228, 3
	s_mov_b64 s[8:9], -1
	v_mov_b64_e32 v[0:1], s[6:7]
	s_and_saveexec_b64 s[4:5], vcc
	s_cbranch_execz .LBB0_971
	v_mov_b32_e32 v0, 0
	global_load_dword v1, v0, s[6:7] sc1
	s_mov_b64 s[12:13], 0
	s_waitcnt vmcnt(0)
	v_cmp_eq_u32_e32 vcc, v1, v2
	s_and_saveexec_b64 s[10:11], vcc
	s_cbranch_execz .LBB0_970
	v_readlane_b32 s12, v228, 2
	v_readlane_b32 s18, v228, 8
	v_readlane_b32 s13, v228, 3
	v_readlane_b32 s19, v228, 9
	s_add_u32 s8, s18, 0x179ed200
	v_readlane_b32 s14, v228, 4
	v_readlane_b32 s15, v228, 5
	s_addc_u32 s9, s19, 0
	s_mov_b32 s22, 1
	s_mov_b64 s[12:13], 0
	v_readlane_b32 s16, v228, 6
	v_readlane_b32 s17, v228, 7
	s_branch .LBB0_963

; __device__ __forceinline__ unsigned xb_ld(unsigned* p)              { return __hip_atomic_load(p, __ATOMIC_RELAXED, __HIP_MEMORY_SCOPE_AGENT); }
; __device__ __forceinline__ unsigned xb_add(unsigned* p, unsigned v) { return __hip_atomic_fetch_add(p, v, __ATOMIC_RELAXED, __HIP_MEMORY_SCOPE_AGENT); }
; #define XB_SPIN(cond, bar) do { unsigned _sp = 0; while (cond) { __builtin_amdgcn_s_sleep(1); \
;     if ((++_sp & 255u) == 0u) { if (xb_ld(&(bar)[XB_TMO])) break; if (_sp > XB_SPIN_CAP) { atomicAdd(&(bar)[XB_TMO], 1u); break; } } } } while (0)
; __device__ __forceinline__ void xcd_barrier(const XcdBarrier& b) {
;     ...
;         unsigned nloc = b.st[0], nx = b.st[1];
;         if (nloc == 0u) { xcd_barrier_complete(bar, b.x, nloc, nx); b.st[0] = nloc; b.st[1] = nx; }
;         const unsigned old = xb_add(&bar[XB_XSUB(b.x)], 1u);
;         const unsigned gen = old / nloc;
;         if (old + 1u == (gen + 1u) * nloc) {
;             __builtin_amdgcn_fence(__ATOMIC_RELEASE, "agent");
;             asm volatile("s_waitcnt vmcnt(0)" ::: "memory");
;             const unsigned og = xb_add(&bar[XB_TOP], 1u);
;             const unsigned tg = og / nx;
;             if (og + 1u == (tg + 1u) * nx) xb_add(&bar[XB_TOPGEN], 1u);
;             else XB_SPIN(xb_ld(&bar[XB_TOPGEN]) == tg, bar);
;             __builtin_amdgcn_fence(__ATOMIC_ACQUIRE, "agent");
;             xb_add(&bar[XB_XGEN(b.x)], 1u);
;             asm volatile("s_waitcnt vmcnt(0)" ::: "memory");
;         } else {
;             XB_SPIN(xb_ld(&bar[XB_XGEN(b.x)]) == gen, bar);
;             __builtin_amdgcn_fence(__ATOMIC_ACQUIRE, "agent");
;             asm volatile("s_waitcnt vmcnt(0)" ::: "memory");
.LBB0_1194:
	s_or_b64 exec, exec, s[6:7]
	v_cvt_f32_u32_e32 v4, v2
	s_waitcnt vmcnt(0)
	v_readfirstlane_b32 s4, v3
	v_sub_u32_e32 v3, 0, v2
	v_rcp_iflag_f32_e32 v4, v4
	v_add_u32_e32 v5, s4, v0
	v_mul_f32_e32 v4, 0x4f7ffffe, v4
	v_cvt_u32_f32_e32 v4, v4
	v_mul_lo_u32 v0, v3, v4
	v_mul_hi_u32 v0, v4, v0
	v_add_u32_e32 v0, v4, v0
	v_mul_hi_u32 v0, v5, v0
	v_mul_lo_u32 v3, v0, v2
	v_sub_u32_e32 v3, v5, v3
	v_add_u32_e32 v4, 1, v0
	v_cmp_ge_u32_e32 vcc, v3, v2
	s_nop 1
	v_cndmask_b32_e32 v0, v0, v4, vcc
	v_sub_u32_e32 v4, v3, v2
	v_cndmask_b32_e32 v3, v3, v4, vcc
	v_add_u32_e32 v4, 1, v0
	v_cmp_ge_u32_e32 vcc, v3, v2
	v_add_u32_e32 v3, 1, v5
	s_nop 0
	v_cndmask_b32_e32 v0, v0, v4, vcc
	v_mul_lo_u32 v4, v2, v0
	v_add_u32_e32 v2, v4, v2
	v_cmp_ne_u32_e32 vcc, v3, v2
	s_and_saveexec_b64 s[4:5], vcc
	s_xor_b64 s[4:5], exec, s[4:5]
	s_cbranch_execz .LBB0_1208
	s_waitcnt lgkmcnt(0)
	buffer_inv sc1
	v_mov_b32_e32 v1, 0x2000
	global_load_dword v1, v1, s[2:3] offset:1024 sc1
	s_add_u32 s10, s2, 0x2400
	s_addc_u32 s11, s3, 0
	s_waitcnt vmcnt(0)
	v_cmp_eq_u32_e32 vcc, v1, v0
	s_and_saveexec_b64 s[6:7], vcc
	s_cbranch_execz .LBB0_1207
	v_readlane_b32 s12, v228, 2
	v_readlane_b32 s14, v228, 4
	v_readlane_b32 s15, v228, 5
	v_readlane_b32 s18, v228, 8
	v_readlane_b32 s19, v228, 9
	s_mov_b64 s[14:15], s[18:19]
	v_readlane_b32 s13, v228, 3
	s_add_u32 s8, s14, 0x179ed200
	s_addc_u32 s9, s15, 0
	s_mov_b32 s22, 1
	s_mov_b64 s[12:13], 0
	v_mov_b32_e32 v1, 0
	v_readlane_b32 s16, v228, 6
	v_readlane_b32 s17, v228, 7
	s_branch .LBB0_1198

; __device__ __forceinline__ unsigned xb_ld(unsigned* p)              { return __hip_atomic_load(p, __ATOMIC_RELAXED, __HIP_MEMORY_SCOPE_AGENT); }
; __device__ __forceinline__ unsigned xb_add(unsigned* p, unsigned v) { return __hip_atomic_fetch_add(p, v, __ATOMIC_RELAXED, __HIP_MEMORY_SCOPE_AGENT); }
; #define XB_SPIN(cond, bar) do { unsigned _sp = 0; while (cond) { __builtin_amdgcn_s_sleep(1); \
;     if ((++_sp & 255u) == 0u) { if (xb_ld(&(bar)[XB_TMO])) break; if (_sp > XB_SPIN_CAP) { atomicAdd(&(bar)[XB_TMO], 1u); break; } } } } while (0)
; __device__ __forceinline__ void xcd_barrier(const XcdBarrier& b) {
;     ...
;         if (old + 1u == (gen + 1u) * nloc) {
;             __builtin_amdgcn_fence(__ATOMIC_RELEASE, "agent");
;             asm volatile("s_waitcnt vmcnt(0)" ::: "memory");
;             const unsigned og = xb_add(&bar[XB_TOP], 1u);
;             const unsigned tg = og / nx;
;             if (og + 1u == (tg + 1u) * nx) xb_add(&bar[XB_TOPGEN], 1u);
;             else XB_SPIN(xb_ld(&bar[XB_TOPGEN]) == tg, bar);
;             __builtin_amdgcn_fence(__ATOMIC_ACQUIRE, "agent");
.LBB0_1211:
	s_or_b64 exec, exec, s[6:7]
	buffer_inv sc1
	v_cvt_f32_u32_e32 v3, v1
	s_waitcnt vmcnt(0)
	v_readfirstlane_b32 s4, v2
	v_rcp_iflag_f32_e32 v3, v3
	s_nop 0
	v_add_u32_e32 v0, s4, v0
	v_add_u32_e32 v4, 1, v0
	v_readlane_b32 s4, v228, 2
	v_mul_f32_e32 v2, 0x4f7ffffe, v3
	v_cvt_u32_f32_e32 v2, v2
	v_sub_u32_e32 v3, 0, v1
	v_readlane_b32 s6, v228, 4
	v_readlane_b32 s7, v228, 5
	v_mul_lo_u32 v3, v3, v2
	v_mul_hi_u32 v3, v2, v3
	v_add_u32_e32 v2, v2, v3
	v_mul_hi_u32 v2, v0, v2
	v_mul_lo_u32 v3, v2, v1
	v_sub_u32_e32 v0, v0, v3
	v_add_u32_e32 v5, 1, v2
	v_cmp_ge_u32_e32 vcc, v0, v1
	v_sub_u32_e32 v3, v0, v1
	v_readlane_b32 s10, v228, 8
	v_cndmask_b32_e32 v2, v2, v5, vcc
	v_cndmask_b32_e32 v0, v0, v3, vcc
	v_add_u32_e32 v3, 1, v2
	v_cmp_ge_u32_e32 vcc, v0, v1
	v_readlane_b32 s11, v228, 9
	s_mov_b64 s[6:7], s[10:11]
	v_cndmask_b32_e32 v2, v2, v3, vcc
	v_mul_lo_u32 v0, v1, v2
	s_add_u32 s6, s6, 0x179f0500
	v_add_u32_e32 v0, v0, v1
	v_readlane_b32 s8, v228, 6
	v_readlane_b32 s9, v228, 7
	s_addc_u32 s7, s7, 0
	v_cmp_ne_u32_e32 vcc, v4, v0
	v_readlane_b32 s5, v228, 3
	s_mov_b64 s[8:9], -1
	v_mov_b64_e32 v[0:1], s[6:7]
	s_and_saveexec_b64 s[4:5], vcc
	s_cbranch_execz .LBB0_1223
	v_mov_b32_e32 v0, 0
	global_load_dword v1, v0, s[6:7] sc1
	s_mov_b64 s[12:13], 0
	s_waitcnt vmcnt(0)
	v_cmp_eq_u32_e32 vcc, v1, v2
	s_and_saveexec_b64 s[10:11], vcc
	s_cbranch_execz .LBB0_1222
	v_readlane_b32 s12, v228, 2
	v_readlane_b32 s14, v228, 4
	v_readlane_b32 s15, v228, 5
	v_readlane_b32 s18, v228, 8
	v_readlane_b32 s19, v228, 9
	s_mov_b64 s[14:15], s[18:19]
	v_readlane_b32 s13, v228, 3
	s_add_u32 s8, s14, 0x179ed200
	s_addc_u32 s9, s15, 0
	s_mov_b32 s22, 1
	s_mov_b64 s[12:13], 0
	v_readlane_b32 s16, v228, 6
	v_readlane_b32 s17, v228, 7
	s_branch .LBB0_1215
